# speedup vs baseline: 1.0089x; 1.0089x over previous
;   __device__ __forceinline__ u16* wt() const { return (u16*)(ws); }
;   __device__ __forceinline__ u16* xres() const { return (u16*)out; }
;   __device__ __forceinline__ unsigned long long* ssq() const { return (unsigned long long*)(ws + 499 * MB); }
; __global__ void __launch_bounds__(512, 2) fwd_megakernel(Params p) {
;     ...
;   const int vb = (int)xb.vbid;
;   if (p.ws == nullptr) grid.sync();
;   xcd_barrier(xb, wv);
;   for (int l = 0; l < DEPTH; ++l) {
;     const u16* wb = p.wt() + (long)(l & 1) * WT_SET;
;     unsigned long long* ssq_mix = p.ssq() + (long)(2 * l) * T_TOK;
;     unsigned long long* ssq_mlp = p.ssq() + (long)(2 * l + 1) * T_TOK;
;     unsigned long long* ssq_nxt = p.ssq() + (long)((2 * l + 2) & 7) * T_TOK;
;     gemm_phase<EPI_PROJ>(p.xres(), DM, wb + O_IN, nullptr, DM, 17, shm, p, nullptr, ssq_mix, nullptr, wv, vb);
.LBB0_112:
	s_or_b64 exec, exec, s[0:1]
	s_cmpk_eq_i32 s37, 0x100
	s_cselect_b64 s[0:1], -1, 0
	s_cmpk_lg_i32 s37, 0x100
	v_writelane_b32 v254, s0, 28
	s_cselect_b64 s[66:67], -1, 0
	s_add_u32 s38, s30, 0xb900000
	v_writelane_b32 v254, s1, 29
	s_addc_u32 s39, s31, 0
	s_and_b32 s0, s24, 0x100
	s_cmp_eq_u32 s0, 0
	s_cselect_b64 s[2:3], -1, 0
	v_writelane_b32 v254, s2, 30
	s_cmp_lg_u32 s0, 0
	s_cselect_b64 s[0:1], -1, 0
	v_writelane_b32 v254, s3, 31
	v_writelane_b32 v254, s0, 32
	v_mov_b32_e32 v2, 0
	s_mov_b32 s19, 0x8000
	v_writelane_b32 v254, s1, 33
	s_add_u32 s0, s30, 0x1c900000
	s_addc_u32 s1, s31, 0
	v_writelane_b32 v254, s0, 34
	s_mov_b32 s85, 0xc000
	s_movk_i32 s76, 0x4000
	v_writelane_b32 v254, s1, 35
	s_add_u32 s0, s30, 0x7900000
	s_addc_u32 s1, s31, 0
	v_writelane_b32 v254, s0, 36
	s_mov_b32 s77, 0x18000
	s_mov_b32 s68, 0x10000
	v_writelane_b32 v254, s1, 37
	v_mov_b32_e32 v160, 0x358637bd
	v_readlane_b32 s0, v254, 10
	s_cmpk_lt_i32 s0, 0x400
	s_cselect_b64 s[0:1], -1, 0
	v_writelane_b32 v254, s0, 38
	v_mov_b32_e32 v185, 1
	v_mov_b32_e32 v163, 0x1f800
	v_writelane_b32 v254, s1, 39
	s_add_u32 s0, s30, 0x1e900000
	s_addc_u32 s1, s31, 0
	s_add_u32 s40, s30, 0x3900000
	v_writelane_b32 v254, s0, 40
	s_addc_u32 s41, s31, 0
	v_mov_b32_e32 v165, 0x1f810
	v_writelane_b32 v254, s1, 41
	s_add_u32 s0, s30, 0x3904000
	s_addc_u32 s1, s31, 0
	v_writelane_b32 v254, s0, 42
	v_mbcnt_hi_u32_b32 v167, -1, v26
	v_mov_b32_e32 v169, 0x10000
	v_writelane_b32 v254, s1, 43
	s_add_u32 s0, s30, 0x3908000
	s_addc_u32 s1, s31, 0
	v_writelane_b32 v254, s0, 44
	v_mov_b32_e32 v161, 0x2200
	v_mov_b32_e32 v6, 0x3f803f80
	v_writelane_b32 v254, s1, 45
	s_add_u32 s0, s30, 0x390c000
	s_addc_u32 s1, s31, 0
	v_writelane_b32 v254, s0, 46
	v_mov_b32_e32 v184, 0xf149f2ca
	s_mov_b32 s69, 0x1c000
	v_writelane_b32 v254, s1, 47
	s_add_u32 s0, s30, 0x3910000
	s_addc_u32 s1, s31, 0
	v_writelane_b32 v254, s0, 48
	s_movk_i32 s88, 0x2200
	s_mov_b32 s89, 0x40000
	v_writelane_b32 v254, s1, 49
	s_add_u32 s0, s30, 0x3914000
	s_addc_u32 s1, s31, 0
	v_writelane_b32 v254, s0, 50
	s_mov_b32 s86, 0x43080000
	s_mov_b32 s87, 0x20000
	v_writelane_b32 v254, s1, 51
	s_add_u32 s0, s30, 0x3918000
	s_addc_u32 s1, s31, 0
	v_writelane_b32 v254, s0, 52
	s_mov_b32 s82, 0x24000
	s_mov_b32 s83, 0x28000
	v_writelane_b32 v254, s1, 53
	s_add_u32 s0, s30, 0x391c000
	s_addc_u32 s1, s31, 0
	v_writelane_b32 v254, s0, 54
	s_mov_b32 s33, 0x2c000
	s_mov_b32 s64, 0x30000
	v_writelane_b32 v254, s1, 55
	s_add_u32 s0, s30, 0x3920000
	s_addc_u32 s1, s31, 0
	v_writelane_b32 v254, s0, 56
	s_mov_b32 s36, 0x34000
	s_mov_b32 s42, 0x38000
	v_writelane_b32 v254, s1, 57
	s_add_u32 s0, s30, 0x3924000
	s_addc_u32 s1, s31, 0
	v_writelane_b32 v254, s0, 58
	s_mov_b64 s[44:45], 0x10000
	s_mov_b64 s[46:47], 0x50000
	v_writelane_b32 v254, s1, 59
	s_add_u32 s0, s30, 0x3928000
	s_addc_u32 s1, s31, 0
	v_writelane_b32 v254, s0, 60
	s_mov_b64 s[48:49], 0x60000
	s_mov_b64 s[34:35], 0x40080
	v_writelane_b32 v254, s1, 61
	s_add_u32 s0, s30, 0x392c000
	s_addc_u32 s1, s31, 0
	v_writelane_b32 v254, s0, 62
	s_mov_b32 s18, 0x3e38aa3b
	s_mov_b64 s[78:79], 0x100000
	v_writelane_b32 v254, s1, 63
	s_add_u32 s0, s30, 0x3930000
	s_addc_u32 s1, s31, 0
	v_writelane_b32 v255, s0, 0
	s_waitcnt lgkmcnt(0)
	s_barrier
	v_writelane_b32 v255, s1, 1
	s_add_u32 s0, s30, 0x3934000
	s_addc_u32 s1, s31, 0
	v_writelane_b32 v255, s0, 2
	s_nop 1
	v_writelane_b32 v255, s1, 3
	s_add_u32 s0, s30, 0x3938000
	s_addc_u32 s1, s31, 0
	v_writelane_b32 v255, s0, 4
	s_nop 1
	v_writelane_b32 v255, s1, 5
	s_add_u32 s0, s30, 0x393c000
	s_addc_u32 s1, s31, 0
	v_writelane_b32 v255, s0, 6
	s_nop 1
	v_writelane_b32 v255, s1, 7
	v_writelane_b32 v255, s56, 8
	s_cmp_lg_u64 s[58:59], 0
	s_cselect_b64 s[0:1], -1, 0
	v_writelane_b32 v255, s57, 9
	v_writelane_b32 v255, s58, 10
	v_writelane_b32 v255, s59, 11
	v_writelane_b32 v255, s60, 12
	v_writelane_b32 v255, s61, 13
	v_writelane_b32 v255, s62, 14
	v_writelane_b32 v255, s63, 15
	v_writelane_b32 v255, s0, 16
	s_mov_b32 s60, 0x14000
	s_mov_b32 s61, 0x800000
	v_writelane_b32 v255, s1, 17
	v_readlane_b32 s0, v254, 11
	v_readlane_b32 s2, v254, 13
	v_readlane_b32 s3, v254, 14
	v_readlane_b32 s1, v254, 12
	s_cmp_lg_u64 s[2:3], 0
	s_cselect_b64 s[0:1], -1, 0
	v_writelane_b32 v255, s0, 18
	s_mov_b64 s[62:63], 0x40000
	s_mov_b32 s56, 0x3f803f80
	v_writelane_b32 v255, s1, 19
	s_lshl_b32 s0, s37, 6
	v_writelane_b32 v255, s0, 20
	s_mov_b32 s0, 1
	v_writelane_b32 v255, s0, 21
	s_mov_b32 s0, 0
	v_writelane_b32 v255, s0, 22
	v_writelane_b32 v255, s0, 23
	v_readlane_b32 s4, v254, 15
	v_readlane_b32 s5, v254, 16
	v_writelane_b32 v255, s1, 24
	v_writelane_b32 v255, s38, 25
	v_readlane_b32 s6, v254, 17
	v_readlane_b32 s7, v254, 18
	v_writelane_b32 v255, s39, 26
	v_writelane_b32 v255, s40, 27
	v_readlane_b32 s8, v254, 19
	v_readlane_b32 s9, v254, 20
	v_writelane_b32 v255, s41, 28
	v_readlane_b32 s10, v254, 21
	v_readlane_b32 s11, v254, 22
	v_readlane_b32 s12, v254, 23
	v_readlane_b32 s13, v254, 24
	v_readlane_b32 s14, v254, 25
	v_readlane_b32 s15, v254, 26
	s_branch .LBB0_115
